# v071 + hand-written P3 residual epilogue in place (all residual and row-scale loads issued up front, no layout change)
# speedup vs baseline: 1.0125x; 1.0125x over previous
; __device__ __forceinline__ unsigned cvt_pk_bf16(float lo, float hi) { unsigned r; asm volatile("v_cvt_pk_bf16_f32 %0, %1, %2" : "=v"(r) : "v"(lo), "v"(hi)); return r; }
; __device__ __forceinline__ float bf_lo(unsigned w) { return __uint_as_float(w << 16); }
; __device__ __forceinline__ float bf_hi(unsigned w) { return __uint_as_float(w & 0xffff0000u); }
;     __device__ __forceinline__ void operator()(EPI_ARGS) const {
;         const int row0 = u.pm * BM + wr * 64 + fr, col0 = u.pn * BM + wc * 32 + 8 * fq;
;         float ssv[8], mxv[8];
; #pragma unroll
;         for (int ai = 0; ai < 2; ++ai) {
;             f32x4 r0[4][2], r1[4][2];
; #pragma unroll
;             for (int m = 0; m < 4; ++m)
; #pragma unroll
;                 for (int bj = 0; bj < 2; ++bj) { const size_t off = (size_t)(row0 + ai * HALF + m * 16) * ldc + col0 + bj * HALF;
;                     if (RES_BF16) { const u32x4 rw = *(const u32x4*)((const bf16*)resid + off); r0[m][bj] = __builtin_bit_cast(f32x4, rw); }
;                     else { r0[m][bj] = *(const f32x4*)((const float*)resid + off); r1[m][bj] = *(const f32x4*)((const float*)resid + off + 4); } }
; #pragma unroll
;             for (int m = 0; m < 4; ++m) { const int row = row0 + ai * HALF + m * 16; const size_t off = (size_t)row * ldc + col0; float ss = 0.f, mx = 0.f;
; #pragma unroll
;                 for (int bj = 0; bj < 2; ++bj) {
;                     f32x4 a0, a1;
;                     if (RES_BF16) { const u32x4 rw = __builtin_bit_cast(u32x4, r0[m][bj]); a0 = (f32x4){bf_lo(rw.x), bf_hi(rw.x), bf_lo(rw.y), bf_hi(rw.y)}; a1 = (f32x4){bf_lo(rw.z), bf_hi(rw.z), bf_lo(rw.w), bf_hi(rw.w)};
;                         if (RES_SCALE) { const float rf = rfac[row]; a0 = a0 * rf; a1 = a1 * rf; } }
;                     else { a0 = r0[m][bj]; a1 = r1[m][bj]; }
;                     const f32x4 v0 = acc[ai][bj][m][0] + a0, v1 = acc[ai][bj][m][1] + a1;
;                     u32x4 w; w.x = cvt_pk_bf16(v0[0], v0[1]); w.y = cvt_pk_bf16(v0[2], v0[3]); w.z = cvt_pk_bf16(v1[0], v1[1]); w.w = cvt_pk_bf16(v1[2], v1[3]); *(u32x4*)(ob + off + bj * HALF) = w;
;                     ss += (v0[0] * v0[0] + v0[1] * v0[1]) + (v0[2] * v0[2] + v0[3] * v0[3]) + (v1[0] * v1[0] + v1[1] * v1[1]) + (v1[2] * v1[2] + v1[3] * v1[3]);
.LBB0_792:
	s_nop 7
	v_lshl_add_u32 v252, s78, 8, v189
	v_lshlrev_b32_e32 v252, 2, v252
	global_load_dword v214, v252, s[66:67]
	global_load_dword v216, v252, s[66:67] offset:64
	global_load_dword v218, v252, s[66:67] offset:128
	global_load_dword v220, v252, s[66:67] offset:192
	global_load_dword v222, v252, s[66:67] offset:512
	global_load_dword v224, v252, s[66:67] offset:576
	global_load_dword v226, v252, s[66:67] offset:640
	global_load_dword v228, v252, s[66:67] offset:704
	v_lshl_add_u32 v245, s78, 8, v189
	v_lshlrev_b32_e32 v245, 13, v245
	v_lshl_or_b32 v246, s24, 8, v190
	v_lshl_add_u32 v245, v246, 1, v245
	global_load_dwordx4 v[98:101], v245, s[12:13]
	global_load_dwordx4 v[110:113], v245, s[12:13] offset:256
	v_add_u32_e32 v246, 0x20000, v245
	global_load_dwordx4 v[122:125], v246, s[12:13]
	global_load_dwordx4 v[134:137], v246, s[12:13] offset:256
	v_add_u32_e32 v255, 0x40000, v245
	global_load_dwordx4 v[138:141], v255, s[12:13]
	global_load_dwordx4 v[150:153], v255, s[12:13] offset:256
	v_add_u32_e32 v246, 0x60000, v245
	global_load_dwordx4 v[154:157], v246, s[12:13]
	global_load_dwordx4 v[162:165], v246, s[12:13] offset:256
	v_add_u32_e32 v255, 0x100000, v245
	global_load_dwordx4 v[166:169], v255, s[12:13]
	global_load_dwordx4 v[170:173], v255, s[12:13] offset:256
	v_add_u32_e32 v246, 0x120000, v245
	global_load_dwordx4 v[174:177], v246, s[12:13]
	global_load_dwordx4 v[178:181], v246, s[12:13] offset:256
	v_add_u32_e32 v255, 0x140000, v245
	global_load_dwordx4 v[198:201], v255, s[12:13]
	global_load_dwordx4 v[202:205], v255, s[12:13] offset:256
	v_add_u32_e32 v246, 0x160000, v245
	global_load_dwordx4 v[206:209], v246, s[12:13]
	global_load_dwordx4 v[210:213], v246, s[12:13] offset:256
	s_waitcnt vmcnt(15)
	v_lshlrev_b32_e32 v248, 16, v98
	v_and_b32_e32 v249, 0xffff0000, v98
	v_lshlrev_b32_e32 v250, 16, v99
	v_and_b32_e32 v251, 0xffff0000, v99
	v_pk_fma_f32 v[146:147], v[214:215], v[248:249], v[146:147] op_sel_hi:[0,1,1]
	v_pk_fma_f32 v[148:149], v[214:215], v[250:251], v[148:149] op_sel_hi:[0,1,1]
	v_lshlrev_b32_e32 v248, 16, v100
	v_and_b32_e32 v249, 0xffff0000, v100
	v_lshlrev_b32_e32 v250, 16, v101
	v_and_b32_e32 v251, 0xffff0000, v101
	v_pk_fma_f32 v[142:143], v[214:215], v[248:249], v[142:143] op_sel_hi:[0,1,1]
	v_pk_fma_f32 v[144:145], v[214:215], v[250:251], v[144:145] op_sel_hi:[0,1,1]
	v_cvt_pk_bf16_f32 v98, v146, v147
	v_cvt_pk_bf16_f32 v99, v148, v149
	v_cvt_pk_bf16_f32 v100, v142, v143
	v_cvt_pk_bf16_f32 v101, v144, v145
	global_store_dwordx4 v245, v[98:101], s[52:53]
	v_mul_f32_e32 v247, v146, v146
	v_fmac_f32_e32 v247, v147, v147
	v_fmac_f32_e32 v247, v148, v148
	v_fmac_f32_e32 v247, v149, v149
	v_mul_f32_e32 v254, v142, v142
	v_fmac_f32_e32 v254, v143, v143
	v_fmac_f32_e32 v254, v144, v144
	v_fmac_f32_e32 v254, v145, v145
	s_waitcnt vmcnt(15)
	v_lshlrev_b32_e32 v248, 16, v110
	v_and_b32_e32 v249, 0xffff0000, v110
	v_lshlrev_b32_e32 v250, 16, v111
	v_and_b32_e32 v251, 0xffff0000, v111
	v_pk_fma_f32 v[130:131], v[214:215], v[248:249], v[130:131] op_sel_hi:[0,1,1]
	v_pk_fma_f32 v[132:133], v[214:215], v[250:251], v[132:133] op_sel_hi:[0,1,1]
	v_lshlrev_b32_e32 v248, 16, v112
	v_and_b32_e32 v249, 0xffff0000, v112
	v_lshlrev_b32_e32 v250, 16, v113
	v_and_b32_e32 v251, 0xffff0000, v113
	v_pk_fma_f32 v[126:127], v[214:215], v[248:249], v[126:127] op_sel_hi:[0,1,1]
	v_pk_fma_f32 v[128:129], v[214:215], v[250:251], v[128:129] op_sel_hi:[0,1,1]
	v_cvt_pk_bf16_f32 v110, v130, v131
	v_cvt_pk_bf16_f32 v111, v132, v133
	v_cvt_pk_bf16_f32 v112, v126, v127
	v_cvt_pk_bf16_f32 v113, v128, v129
	global_store_dwordx4 v245, v[110:113], s[52:53] offset:256
	v_fmac_f32_e32 v247, v130, v130
	v_fmac_f32_e32 v247, v131, v131
	v_fmac_f32_e32 v247, v132, v132
	v_fmac_f32_e32 v247, v133, v133
	v_fmac_f32_e32 v254, v126, v126
	v_fmac_f32_e32 v254, v127, v127
	v_fmac_f32_e32 v254, v128, v128
	v_fmac_f32_e32 v254, v129, v129
	v_add_f32_e32 v146, v247, v254
	s_waitcnt vmcnt(15)
	v_lshlrev_b32_e32 v248, 16, v122
	v_and_b32_e32 v249, 0xffff0000, v122
	v_lshlrev_b32_e32 v250, 16, v123
	v_and_b32_e32 v251, 0xffff0000, v123
	v_pk_fma_f32 v[118:119], v[216:217], v[248:249], v[118:119] op_sel_hi:[0,1,1]
	v_pk_fma_f32 v[120:121], v[216:217], v[250:251], v[120:121] op_sel_hi:[0,1,1]
	v_lshlrev_b32_e32 v248, 16, v124
	v_and_b32_e32 v249, 0xffff0000, v124
	v_lshlrev_b32_e32 v250, 16, v125
	v_and_b32_e32 v251, 0xffff0000, v125
	v_pk_fma_f32 v[114:115], v[216:217], v[248:249], v[114:115] op_sel_hi:[0,1,1]
	v_pk_fma_f32 v[116:117], v[216:217], v[250:251], v[116:117] op_sel_hi:[0,1,1]
	v_cvt_pk_bf16_f32 v122, v118, v119
	v_cvt_pk_bf16_f32 v123, v120, v121
	v_cvt_pk_bf16_f32 v124, v114, v115
	v_cvt_pk_bf16_f32 v125, v116, v117
	v_add_u32_e32 v246, 0x20000, v245
	global_store_dwordx4 v246, v[122:125], s[52:53]
	v_mul_f32_e32 v247, v118, v118
	v_fmac_f32_e32 v247, v119, v119
	v_fmac_f32_e32 v247, v120, v120
	v_fmac_f32_e32 v247, v121, v121
	v_mul_f32_e32 v254, v114, v114
	v_fmac_f32_e32 v254, v115, v115
	v_fmac_f32_e32 v254, v116, v116
	v_fmac_f32_e32 v254, v117, v117
	s_waitcnt vmcnt(15)
; __device__ __forceinline__ unsigned cvt_pk_bf16(float lo, float hi) { unsigned r; asm volatile("v_cvt_pk_bf16_f32 %0, %1, %2" : "=v"(r) : "v"(lo), "v"(hi)); return r; }
; __device__ __forceinline__ float bf_lo(unsigned w) { return __uint_as_float(w << 16); }
; __device__ __forceinline__ float bf_hi(unsigned w) { return __uint_as_float(w & 0xffff0000u); }
;     __device__ __forceinline__ void operator()(EPI_ARGS) const {
;     ...
;             for (int m = 0; m < 4; ++m) { const int row = row0 + ai * HALF + m * 16; const size_t off = (size_t)row * ldc + col0; float ss = 0.f, mx = 0.f;
; #pragma unroll
;                 for (int bj = 0; bj < 2; ++bj) {
;                     f32x4 a0, a1;
;                     if (RES_BF16) { const u32x4 rw = __builtin_bit_cast(u32x4, r0[m][bj]); a0 = (f32x4){bf_lo(rw.x), bf_hi(rw.x), bf_lo(rw.y), bf_hi(rw.y)}; a1 = (f32x4){bf_lo(rw.z), bf_hi(rw.z), bf_lo(rw.w), bf_hi(rw.w)};
;                         if (RES_SCALE) { const float rf = rfac[row]; a0 = a0 * rf; a1 = a1 * rf; } }
;                     else { a0 = r0[m][bj]; a1 = r1[m][bj]; }
;                     const f32x4 v0 = acc[ai][bj][m][0] + a0, v1 = acc[ai][bj][m][1] + a1;
;                     u32x4 w; w.x = cvt_pk_bf16(v0[0], v0[1]); w.y = cvt_pk_bf16(v0[2], v0[3]); w.z = cvt_pk_bf16(v1[0], v1[1]); w.w = cvt_pk_bf16(v1[2], v1[3]); *(u32x4*)(ob + off + bj * HALF) = w;
;                     ss += (v0[0] * v0[0] + v0[1] * v0[1]) + (v0[2] * v0[2] + v0[3] * v0[3]) + (v1[0] * v1[0] + v1[1] * v1[1]) + (v1[2] * v1[2] + v1[3] * v1[3]);
;                     if (rowmax) mx = fmaxf(mx, fmaxf(fmaxf(fmaxf(fabsf(v0[0]), fabsf(v0[1])), fmaxf(fabsf(v0[2]), fabsf(v0[3]))), fmaxf(fmaxf(fabsf(v1[0]), fabsf(v1[1])), fmaxf(fabsf(v1[2]), fabsf(v1[3]))))); }
	v_lshlrev_b32_e32 v248, 16, v134
	v_and_b32_e32 v249, 0xffff0000, v134
	v_lshlrev_b32_e32 v250, 16, v135
	v_and_b32_e32 v251, 0xffff0000, v135
	v_pk_fma_f32 v[106:107], v[216:217], v[248:249], v[106:107] op_sel_hi:[0,1,1]
	v_pk_fma_f32 v[108:109], v[216:217], v[250:251], v[108:109] op_sel_hi:[0,1,1]
	v_lshlrev_b32_e32 v248, 16, v136
	v_and_b32_e32 v249, 0xffff0000, v136
	v_lshlrev_b32_e32 v250, 16, v137
	v_and_b32_e32 v251, 0xffff0000, v137
	v_pk_fma_f32 v[102:103], v[216:217], v[248:249], v[102:103] op_sel_hi:[0,1,1]
	v_pk_fma_f32 v[104:105], v[216:217], v[250:251], v[104:105] op_sel_hi:[0,1,1]
	v_cvt_pk_bf16_f32 v134, v106, v107
	v_cvt_pk_bf16_f32 v135, v108, v109
	v_cvt_pk_bf16_f32 v136, v102, v103
	v_cvt_pk_bf16_f32 v137, v104, v105
	v_add_u32_e32 v255, 0x20000, v245
	global_store_dwordx4 v255, v[134:137], s[52:53] offset:256
	v_fmac_f32_e32 v247, v106, v106
	v_fmac_f32_e32 v247, v107, v107
	v_fmac_f32_e32 v247, v108, v108
	v_fmac_f32_e32 v247, v109, v109
	v_fmac_f32_e32 v254, v102, v102
	v_fmac_f32_e32 v254, v103, v103
	v_fmac_f32_e32 v254, v104, v104
	v_fmac_f32_e32 v254, v105, v105
	v_add_f32_e32 v118, v247, v254
	s_waitcnt vmcnt(15)
	v_lshlrev_b32_e32 v248, 16, v138
	v_and_b32_e32 v249, 0xffff0000, v138
	v_lshlrev_b32_e32 v250, 16, v139
	v_and_b32_e32 v251, 0xffff0000, v139
	v_pk_fma_f32 v[94:95], v[218:219], v[248:249], v[94:95] op_sel_hi:[0,1,1]
	v_pk_fma_f32 v[96:97], v[218:219], v[250:251], v[96:97] op_sel_hi:[0,1,1]
	v_lshlrev_b32_e32 v248, 16, v140
	v_and_b32_e32 v249, 0xffff0000, v140
	v_lshlrev_b32_e32 v250, 16, v141
	v_and_b32_e32 v251, 0xffff0000, v141
	v_pk_fma_f32 v[90:91], v[218:219], v[248:249], v[90:91] op_sel_hi:[0,1,1]
	v_pk_fma_f32 v[92:93], v[218:219], v[250:251], v[92:93] op_sel_hi:[0,1,1]
	v_cvt_pk_bf16_f32 v138, v94, v95
	v_cvt_pk_bf16_f32 v139, v96, v97
	v_cvt_pk_bf16_f32 v140, v90, v91
	v_cvt_pk_bf16_f32 v141, v92, v93
	v_add_u32_e32 v246, 0x40000, v245
	global_store_dwordx4 v246, v[138:141], s[52:53]
	v_mul_f32_e32 v247, v94, v94
	v_fmac_f32_e32 v247, v95, v95
	v_fmac_f32_e32 v247, v96, v96
	v_fmac_f32_e32 v247, v97, v97
	v_mul_f32_e32 v254, v90, v90
	v_fmac_f32_e32 v254, v91, v91
	v_fmac_f32_e32 v254, v92, v92
	v_fmac_f32_e32 v254, v93, v93
	s_waitcnt vmcnt(15)
	v_lshlrev_b32_e32 v248, 16, v150
	v_and_b32_e32 v249, 0xffff0000, v150
	v_lshlrev_b32_e32 v250, 16, v151
	v_and_b32_e32 v251, 0xffff0000, v151
	v_pk_fma_f32 v[86:87], v[218:219], v[248:249], v[86:87] op_sel_hi:[0,1,1]
	v_pk_fma_f32 v[88:89], v[218:219], v[250:251], v[88:89] op_sel_hi:[0,1,1]
	v_lshlrev_b32_e32 v248, 16, v152
	v_and_b32_e32 v249, 0xffff0000, v152
	v_lshlrev_b32_e32 v250, 16, v153
	v_and_b32_e32 v251, 0xffff0000, v153
	v_pk_fma_f32 v[82:83], v[218:219], v[248:249], v[82:83] op_sel_hi:[0,1,1]
	v_pk_fma_f32 v[84:85], v[218:219], v[250:251], v[84:85] op_sel_hi:[0,1,1]
	v_cvt_pk_bf16_f32 v150, v86, v87
	v_cvt_pk_bf16_f32 v151, v88, v89
	v_cvt_pk_bf16_f32 v152, v82, v83
	v_cvt_pk_bf16_f32 v153, v84, v85
	v_add_u32_e32 v255, 0x40000, v245
	global_store_dwordx4 v255, v[150:153], s[52:53] offset:256
	v_fmac_f32_e32 v247, v86, v86
	v_fmac_f32_e32 v247, v87, v87
	v_fmac_f32_e32 v247, v88, v88
	v_fmac_f32_e32 v247, v89, v89
	v_fmac_f32_e32 v254, v82, v82
	v_fmac_f32_e32 v254, v83, v83
	v_fmac_f32_e32 v254, v84, v84
	v_fmac_f32_e32 v254, v85, v85
	v_add_f32_e32 v94, v247, v254
	s_waitcnt vmcnt(15)
	v_lshlrev_b32_e32 v248, 16, v154
	v_and_b32_e32 v249, 0xffff0000, v154
	v_lshlrev_b32_e32 v250, 16, v155
	v_and_b32_e32 v251, 0xffff0000, v155
	v_pk_fma_f32 v[78:79], v[220:221], v[248:249], v[78:79] op_sel_hi:[0,1,1]
	v_pk_fma_f32 v[80:81], v[220:221], v[250:251], v[80:81] op_sel_hi:[0,1,1]
	v_lshlrev_b32_e32 v248, 16, v156
	v_and_b32_e32 v249, 0xffff0000, v156
	v_lshlrev_b32_e32 v250, 16, v157
	v_and_b32_e32 v251, 0xffff0000, v157
	v_pk_fma_f32 v[74:75], v[220:221], v[248:249], v[74:75] op_sel_hi:[0,1,1]
	v_pk_fma_f32 v[76:77], v[220:221], v[250:251], v[76:77] op_sel_hi:[0,1,1]
	v_cvt_pk_bf16_f32 v154, v78, v79
	v_cvt_pk_bf16_f32 v155, v80, v81
	v_cvt_pk_bf16_f32 v156, v74, v75
	v_cvt_pk_bf16_f32 v157, v76, v77
	v_add_u32_e32 v246, 0x60000, v245
	global_store_dwordx4 v246, v[154:157], s[52:53]
	v_mul_f32_e32 v247, v78, v78
	v_fmac_f32_e32 v247, v79, v79
	v_fmac_f32_e32 v247, v80, v80
	v_fmac_f32_e32 v247, v81, v81
	v_mul_f32_e32 v254, v74, v74
	v_fmac_f32_e32 v254, v75, v75
	v_fmac_f32_e32 v254, v76, v76
	v_fmac_f32_e32 v254, v77, v77
	s_waitcnt vmcnt(15)
	v_lshlrev_b32_e32 v248, 16, v162
	v_and_b32_e32 v249, 0xffff0000, v162
	v_lshlrev_b32_e32 v250, 16, v163
	v_and_b32_e32 v251, 0xffff0000, v163
	v_pk_fma_f32 v[70:71], v[220:221], v[248:249], v[70:71] op_sel_hi:[0,1,1]
	v_pk_fma_f32 v[72:73], v[220:221], v[250:251], v[72:73] op_sel_hi:[0,1,1]
	v_lshlrev_b32_e32 v248, 16, v164
	v_and_b32_e32 v249, 0xffff0000, v164
	v_lshlrev_b32_e32 v250, 16, v165
	v_and_b32_e32 v251, 0xffff0000, v165
	v_pk_fma_f32 v[66:67], v[220:221], v[248:249], v[66:67] op_sel_hi:[0,1,1]
	v_pk_fma_f32 v[68:69], v[220:221], v[250:251], v[68:69] op_sel_hi:[0,1,1]
	v_cvt_pk_bf16_f32 v162, v70, v71
	v_cvt_pk_bf16_f32 v163, v72, v73
	v_cvt_pk_bf16_f32 v164, v66, v67
	v_cvt_pk_bf16_f32 v165, v68, v69
	v_add_u32_e32 v255, 0x60000, v245
	global_store_dwordx4 v255, v[162:165], s[52:53] offset:256
	v_fmac_f32_e32 v247, v70, v70
	v_fmac_f32_e32 v247, v71, v71
	v_fmac_f32_e32 v247, v72, v72
	v_fmac_f32_e32 v247, v73, v73
	v_fmac_f32_e32 v254, v66, v66
	v_fmac_f32_e32 v254, v67, v67
	v_fmac_f32_e32 v254, v68, v68
	v_fmac_f32_e32 v254, v69, v69
	v_add_f32_e32 v78, v247, v254
	s_waitcnt vmcnt(15)
; __device__ __forceinline__ unsigned cvt_pk_bf16(float lo, float hi) { unsigned r; asm volatile("v_cvt_pk_bf16_f32 %0, %1, %2" : "=v"(r) : "v"(lo), "v"(hi)); return r; }
; __device__ __forceinline__ float bf_lo(unsigned w) { return __uint_as_float(w << 16); }
; __device__ __forceinline__ float bf_hi(unsigned w) { return __uint_as_float(w & 0xffff0000u); }
;     __device__ __forceinline__ void operator()(EPI_ARGS) const {
;     ...
;             for (int m = 0; m < 4; ++m) { const int row = row0 + ai * HALF + m * 16; const size_t off = (size_t)row * ldc + col0; float ss = 0.f, mx = 0.f;
; #pragma unroll
;                 for (int bj = 0; bj < 2; ++bj) {
;                     f32x4 a0, a1;
;                     if (RES_BF16) { const u32x4 rw = __builtin_bit_cast(u32x4, r0[m][bj]); a0 = (f32x4){bf_lo(rw.x), bf_hi(rw.x), bf_lo(rw.y), bf_hi(rw.y)}; a1 = (f32x4){bf_lo(rw.z), bf_hi(rw.z), bf_lo(rw.w), bf_hi(rw.w)};
;                         if (RES_SCALE) { const float rf = rfac[row]; a0 = a0 * rf; a1 = a1 * rf; } }
;                     else { a0 = r0[m][bj]; a1 = r1[m][bj]; }
;                     const f32x4 v0 = acc[ai][bj][m][0] + a0, v1 = acc[ai][bj][m][1] + a1;
;                     u32x4 w; w.x = cvt_pk_bf16(v0[0], v0[1]); w.y = cvt_pk_bf16(v0[2], v0[3]); w.z = cvt_pk_bf16(v1[0], v1[1]); w.w = cvt_pk_bf16(v1[2], v1[3]); *(u32x4*)(ob + off + bj * HALF) = w;
;                     ss += (v0[0] * v0[0] + v0[1] * v0[1]) + (v0[2] * v0[2] + v0[3] * v0[3]) + (v1[0] * v1[0] + v1[1] * v1[1]) + (v1[2] * v1[2] + v1[3] * v1[3]);
;                     if (rowmax) mx = fmaxf(mx, fmaxf(fmaxf(fmaxf(fabsf(v0[0]), fabsf(v0[1])), fmaxf(fabsf(v0[2]), fabsf(v0[3]))), fmaxf(fmaxf(fabsf(v1[0]), fabsf(v1[1])), fmaxf(fabsf(v1[2]), fabsf(v1[3]))))); }
	v_lshlrev_b32_e32 v248, 16, v166
	v_and_b32_e32 v249, 0xffff0000, v166
	v_lshlrev_b32_e32 v250, 16, v167
	v_and_b32_e32 v251, 0xffff0000, v167
	v_pk_fma_f32 v[62:63], v[222:223], v[248:249], v[62:63] op_sel_hi:[0,1,1]
	v_pk_fma_f32 v[64:65], v[222:223], v[250:251], v[64:65] op_sel_hi:[0,1,1]
	v_lshlrev_b32_e32 v248, 16, v168
	v_and_b32_e32 v249, 0xffff0000, v168
	v_lshlrev_b32_e32 v250, 16, v169
	v_and_b32_e32 v251, 0xffff0000, v169
	v_pk_fma_f32 v[58:59], v[222:223], v[248:249], v[58:59] op_sel_hi:[0,1,1]
	v_pk_fma_f32 v[60:61], v[222:223], v[250:251], v[60:61] op_sel_hi:[0,1,1]
	v_cvt_pk_bf16_f32 v166, v62, v63
	v_cvt_pk_bf16_f32 v167, v64, v65
	v_cvt_pk_bf16_f32 v168, v58, v59
	v_cvt_pk_bf16_f32 v169, v60, v61
	v_add_u32_e32 v246, 0x100000, v245
	global_store_dwordx4 v246, v[166:169], s[52:53]
	v_mul_f32_e32 v247, v62, v62
	v_fmac_f32_e32 v247, v63, v63
	v_fmac_f32_e32 v247, v64, v64
	v_fmac_f32_e32 v247, v65, v65
	v_mul_f32_e32 v254, v58, v58
	v_fmac_f32_e32 v254, v59, v59
	v_fmac_f32_e32 v254, v60, v60
	v_fmac_f32_e32 v254, v61, v61
	s_waitcnt vmcnt(15)
	v_lshlrev_b32_e32 v248, 16, v170
	v_and_b32_e32 v249, 0xffff0000, v170
	v_lshlrev_b32_e32 v250, 16, v171
	v_and_b32_e32 v251, 0xffff0000, v171
	v_pk_fma_f32 v[54:55], v[222:223], v[248:249], v[54:55] op_sel_hi:[0,1,1]
	v_pk_fma_f32 v[56:57], v[222:223], v[250:251], v[56:57] op_sel_hi:[0,1,1]
	v_lshlrev_b32_e32 v248, 16, v172
	v_and_b32_e32 v249, 0xffff0000, v172
	v_lshlrev_b32_e32 v250, 16, v173
	v_and_b32_e32 v251, 0xffff0000, v173
	v_pk_fma_f32 v[50:51], v[222:223], v[248:249], v[50:51] op_sel_hi:[0,1,1]
	v_pk_fma_f32 v[52:53], v[222:223], v[250:251], v[52:53] op_sel_hi:[0,1,1]
	v_cvt_pk_bf16_f32 v170, v54, v55
	v_cvt_pk_bf16_f32 v171, v56, v57
	v_cvt_pk_bf16_f32 v172, v50, v51
	v_cvt_pk_bf16_f32 v173, v52, v53
	v_add_u32_e32 v255, 0x100000, v245
	global_store_dwordx4 v255, v[170:173], s[52:53] offset:256
	v_fmac_f32_e32 v247, v54, v54
	v_fmac_f32_e32 v247, v55, v55
	v_fmac_f32_e32 v247, v56, v56
	v_fmac_f32_e32 v247, v57, v57
	v_fmac_f32_e32 v254, v50, v50
	v_fmac_f32_e32 v254, v51, v51
	v_fmac_f32_e32 v254, v52, v52
	v_fmac_f32_e32 v254, v53, v53
	v_add_f32_e32 v62, v247, v254
	s_waitcnt vmcnt(15)
	v_lshlrev_b32_e32 v248, 16, v174
	v_and_b32_e32 v249, 0xffff0000, v174
	v_lshlrev_b32_e32 v250, 16, v175
	v_and_b32_e32 v251, 0xffff0000, v175
	v_pk_fma_f32 v[46:47], v[224:225], v[248:249], v[46:47] op_sel_hi:[0,1,1]
	v_pk_fma_f32 v[48:49], v[224:225], v[250:251], v[48:49] op_sel_hi:[0,1,1]
	v_lshlrev_b32_e32 v248, 16, v176
	v_and_b32_e32 v249, 0xffff0000, v176
	v_lshlrev_b32_e32 v250, 16, v177
	v_and_b32_e32 v251, 0xffff0000, v177
	v_pk_fma_f32 v[42:43], v[224:225], v[248:249], v[42:43] op_sel_hi:[0,1,1]
	v_pk_fma_f32 v[44:45], v[224:225], v[250:251], v[44:45] op_sel_hi:[0,1,1]
	v_cvt_pk_bf16_f32 v174, v46, v47
	v_cvt_pk_bf16_f32 v175, v48, v49
	v_cvt_pk_bf16_f32 v176, v42, v43
	v_cvt_pk_bf16_f32 v177, v44, v45
	v_add_u32_e32 v246, 0x120000, v245
	global_store_dwordx4 v246, v[174:177], s[52:53]
	v_mul_f32_e32 v247, v46, v46
	v_fmac_f32_e32 v247, v47, v47
	v_fmac_f32_e32 v247, v48, v48
	v_fmac_f32_e32 v247, v49, v49
	v_mul_f32_e32 v254, v42, v42
	v_fmac_f32_e32 v254, v43, v43
	v_fmac_f32_e32 v254, v44, v44
	v_fmac_f32_e32 v254, v45, v45
	s_waitcnt vmcnt(15)
	v_lshlrev_b32_e32 v248, 16, v178
	v_and_b32_e32 v249, 0xffff0000, v178
	v_lshlrev_b32_e32 v250, 16, v179
	v_and_b32_e32 v251, 0xffff0000, v179
	v_pk_fma_f32 v[38:39], v[224:225], v[248:249], v[38:39] op_sel_hi:[0,1,1]
	v_pk_fma_f32 v[40:41], v[224:225], v[250:251], v[40:41] op_sel_hi:[0,1,1]
	v_lshlrev_b32_e32 v248, 16, v180
	v_and_b32_e32 v249, 0xffff0000, v180
	v_lshlrev_b32_e32 v250, 16, v181
	v_and_b32_e32 v251, 0xffff0000, v181
	v_pk_fma_f32 v[34:35], v[224:225], v[248:249], v[34:35] op_sel_hi:[0,1,1]
	v_pk_fma_f32 v[36:37], v[224:225], v[250:251], v[36:37] op_sel_hi:[0,1,1]
	v_cvt_pk_bf16_f32 v178, v38, v39
	v_cvt_pk_bf16_f32 v179, v40, v41
	v_cvt_pk_bf16_f32 v180, v34, v35
	v_cvt_pk_bf16_f32 v181, v36, v37
	v_add_u32_e32 v255, 0x120000, v245
	global_store_dwordx4 v255, v[178:181], s[52:53] offset:256
	v_fmac_f32_e32 v247, v38, v38
	v_fmac_f32_e32 v247, v39, v39
	v_fmac_f32_e32 v247, v40, v40
	v_fmac_f32_e32 v247, v41, v41
	v_fmac_f32_e32 v254, v34, v34
	v_fmac_f32_e32 v254, v35, v35
	v_fmac_f32_e32 v254, v36, v36
	v_fmac_f32_e32 v254, v37, v37
	v_add_f32_e32 v46, v247, v254
	s_waitcnt vmcnt(15)
	v_lshlrev_b32_e32 v248, 16, v198
	v_and_b32_e32 v249, 0xffff0000, v198
	v_lshlrev_b32_e32 v250, 16, v199
	v_and_b32_e32 v251, 0xffff0000, v199
	v_pk_fma_f32 v[30:31], v[226:227], v[248:249], v[30:31] op_sel_hi:[0,1,1]
	v_pk_fma_f32 v[32:33], v[226:227], v[250:251], v[32:33] op_sel_hi:[0,1,1]
	v_lshlrev_b32_e32 v248, 16, v200
	v_and_b32_e32 v249, 0xffff0000, v200
	v_lshlrev_b32_e32 v250, 16, v201
	v_and_b32_e32 v251, 0xffff0000, v201
	v_pk_fma_f32 v[26:27], v[226:227], v[248:249], v[26:27] op_sel_hi:[0,1,1]
	v_pk_fma_f32 v[28:29], v[226:227], v[250:251], v[28:29] op_sel_hi:[0,1,1]
	v_cvt_pk_bf16_f32 v198, v30, v31
	v_cvt_pk_bf16_f32 v199, v32, v33
	v_cvt_pk_bf16_f32 v200, v26, v27
	v_cvt_pk_bf16_f32 v201, v28, v29
	v_add_u32_e32 v246, 0x140000, v245
	global_store_dwordx4 v246, v[198:201], s[52:53]
	v_mul_f32_e32 v247, v30, v30
	v_fmac_f32_e32 v247, v31, v31
	v_fmac_f32_e32 v247, v32, v32
	v_fmac_f32_e32 v247, v33, v33
	v_mul_f32_e32 v254, v26, v26
	v_fmac_f32_e32 v254, v27, v27
	v_fmac_f32_e32 v254, v28, v28
	v_fmac_f32_e32 v254, v29, v29
	s_waitcnt vmcnt(15)
;     __device__ __forceinline__ void operator()(EPI_ARGS) const {
;     ...
;             for (int m = 0; m < 4; ++m) { const int row = row0 + ai * HALF + m * 16; const size_t off = (size_t)row * ldc + col0; float ss = 0.f, mx = 0.f;
; #pragma unroll
;                 for (int bj = 0; bj < 2; ++bj) {
;                     f32x4 a0, a1;
;                     if (RES_BF16) { const u32x4 rw = __builtin_bit_cast(u32x4, r0[m][bj]); a0 = (f32x4){bf_lo(rw.x), bf_hi(rw.x), bf_lo(rw.y), bf_hi(rw.y)}; a1 = (f32x4){bf_lo(rw.z), bf_hi(rw.z), bf_lo(rw.w), bf_hi(rw.w)};
;                         if (RES_SCALE) { const float rf = rfac[row]; a0 = a0 * rf; a1 = a1 * rf; } }
;                     else { a0 = r0[m][bj]; a1 = r1[m][bj]; }
;                     const f32x4 v0 = acc[ai][bj][m][0] + a0, v1 = acc[ai][bj][m][1] + a1;
;                     u32x4 w; w.x = cvt_pk_bf16(v0[0], v0[1]); w.y = cvt_pk_bf16(v0[2], v0[3]); w.z = cvt_pk_bf16(v1[0], v1[1]); w.w = cvt_pk_bf16(v1[2], v1[3]); *(u32x4*)(ob + off + bj * HALF) = w;
;                     ss += (v0[0] * v0[0] + v0[1] * v0[1]) + (v0[2] * v0[2] + v0[3] * v0[3]) + (v1[0] * v1[0] + v1[1] * v1[1]) + (v1[2] * v1[2] + v1[3] * v1[3]);
;                     if (rowmax) mx = fmaxf(mx, fmaxf(fmaxf(fmaxf(fabsf(v0[0]), fabsf(v0[1])), fmaxf(fabsf(v0[2]), fabsf(v0[3]))), fmaxf(fmaxf(fabsf(v1[0]), fabsf(v1[1])), fmaxf(fabsf(v1[2]), fabsf(v1[3]))))); }
;                 ss += __shfl_xor(ss, 16); ss += __shfl_xor(ss, 32); ssv[ai * 4 + m] = ss;
;                 if (rowmax) { mx = fmaxf(mx, __shfl_xor(mx, 16)); mx = fmaxf(mx, __shfl_xor(mx, 32)); } mxv[ai * 4 + m] = mx; }
;             asm volatile("" ::: "memory"); }
;         float s0 = 0.f, s1 = 0.f, m0 = 0.f, m1 = 0.f;
; #pragma unroll
;         for (int k = 0; k < 8; ++k) if ((k >> 1) == fq) { if (k & 1) { s1 = ssv[k]; m1 = mxv[k]; } else { s0 = ssv[k]; m0 = mxv[k]; } }
;         const int rq = row0 + (fq >> 1) * HALF + (fq & 1) * 32;
;         __hip_atomic_fetch_add(rowsq + rq, s0, __ATOMIC_RELAXED, __HIP_MEMORY_SCOPE_AGENT); __hip_atomic_fetch_add(rowsq + rq + 16, s1, __ATOMIC_RELAXED, __HIP_MEMORY_SCOPE_AGENT);
;         if (rowmax) { __hip_atomic_fetch_max(rowmax + rq, __float_as_uint(m0), __ATOMIC_RELAXED, __HIP_MEMORY_SCOPE_AGENT); __hip_atomic_fetch_max(rowmax + rq + 16, __float_as_uint(m1), __ATOMIC_RELAXED, __HIP_MEMORY_SCOPE_AGENT); }
	v_lshlrev_b32_e32 v248, 16, v202
	v_and_b32_e32 v249, 0xffff0000, v202
	v_lshlrev_b32_e32 v250, 16, v203
	v_and_b32_e32 v251, 0xffff0000, v203
	v_pk_fma_f32 v[22:23], v[226:227], v[248:249], v[22:23] op_sel_hi:[0,1,1]
	v_pk_fma_f32 v[24:25], v[226:227], v[250:251], v[24:25] op_sel_hi:[0,1,1]
	v_lshlrev_b32_e32 v248, 16, v204
	v_and_b32_e32 v249, 0xffff0000, v204
	v_lshlrev_b32_e32 v250, 16, v205
	v_and_b32_e32 v251, 0xffff0000, v205
	v_pk_fma_f32 v[18:19], v[226:227], v[248:249], v[18:19] op_sel_hi:[0,1,1]
	v_pk_fma_f32 v[20:21], v[226:227], v[250:251], v[20:21] op_sel_hi:[0,1,1]
	v_cvt_pk_bf16_f32 v202, v22, v23
	v_cvt_pk_bf16_f32 v203, v24, v25
	v_cvt_pk_bf16_f32 v204, v18, v19
	v_cvt_pk_bf16_f32 v205, v20, v21
	v_add_u32_e32 v255, 0x140000, v245
	global_store_dwordx4 v255, v[202:205], s[52:53] offset:256
	v_fmac_f32_e32 v247, v22, v22
	v_fmac_f32_e32 v247, v23, v23
	v_fmac_f32_e32 v247, v24, v24
	v_fmac_f32_e32 v247, v25, v25
	v_fmac_f32_e32 v254, v18, v18
	v_fmac_f32_e32 v254, v19, v19
	v_fmac_f32_e32 v254, v20, v20
	v_fmac_f32_e32 v254, v21, v21
	v_add_f32_e32 v30, v247, v254
	s_waitcnt vmcnt(15)
	v_lshlrev_b32_e32 v248, 16, v206
	v_and_b32_e32 v249, 0xffff0000, v206
	v_lshlrev_b32_e32 v250, 16, v207
	v_and_b32_e32 v251, 0xffff0000, v207
	v_pk_fma_f32 v[14:15], v[228:229], v[248:249], v[14:15] op_sel_hi:[0,1,1]
	v_pk_fma_f32 v[16:17], v[228:229], v[250:251], v[16:17] op_sel_hi:[0,1,1]
	v_lshlrev_b32_e32 v248, 16, v208
	v_and_b32_e32 v249, 0xffff0000, v208
	v_lshlrev_b32_e32 v250, 16, v209
	v_and_b32_e32 v251, 0xffff0000, v209
	v_pk_fma_f32 v[10:11], v[228:229], v[248:249], v[10:11] op_sel_hi:[0,1,1]
	v_pk_fma_f32 v[12:13], v[228:229], v[250:251], v[12:13] op_sel_hi:[0,1,1]
	v_cvt_pk_bf16_f32 v206, v14, v15
	v_cvt_pk_bf16_f32 v207, v16, v17
	v_cvt_pk_bf16_f32 v208, v10, v11
	v_cvt_pk_bf16_f32 v209, v12, v13
	v_add_u32_e32 v246, 0x160000, v245
	global_store_dwordx4 v246, v[206:209], s[52:53]
	v_mul_f32_e32 v247, v14, v14
	v_fmac_f32_e32 v247, v15, v15
	v_fmac_f32_e32 v247, v16, v16
	v_fmac_f32_e32 v247, v17, v17
	v_mul_f32_e32 v254, v10, v10
	v_fmac_f32_e32 v254, v11, v11
	v_fmac_f32_e32 v254, v12, v12
	v_fmac_f32_e32 v254, v13, v13
	s_waitcnt vmcnt(15)
	v_lshlrev_b32_e32 v248, 16, v210
	v_and_b32_e32 v249, 0xffff0000, v210
	v_lshlrev_b32_e32 v250, 16, v211
	v_and_b32_e32 v251, 0xffff0000, v211
	v_pk_fma_f32 v[6:7], v[228:229], v[248:249], v[6:7] op_sel_hi:[0,1,1]
	v_pk_fma_f32 v[8:9], v[228:229], v[250:251], v[8:9] op_sel_hi:[0,1,1]
	v_lshlrev_b32_e32 v248, 16, v212
	v_and_b32_e32 v249, 0xffff0000, v212
	v_lshlrev_b32_e32 v250, 16, v213
	v_and_b32_e32 v251, 0xffff0000, v213
	v_pk_fma_f32 v[2:3], v[228:229], v[248:249], v[2:3] op_sel_hi:[0,1,1]
	v_pk_fma_f32 v[4:5], v[228:229], v[250:251], v[4:5] op_sel_hi:[0,1,1]
	v_cvt_pk_bf16_f32 v210, v6, v7
	v_cvt_pk_bf16_f32 v211, v8, v9
	v_cvt_pk_bf16_f32 v212, v2, v3
	v_cvt_pk_bf16_f32 v213, v4, v5
	v_add_u32_e32 v255, 0x160000, v245
	global_store_dwordx4 v255, v[210:213], s[52:53] offset:256
	v_fmac_f32_e32 v247, v6, v6
	v_fmac_f32_e32 v247, v7, v7
	v_fmac_f32_e32 v247, v8, v8
	v_fmac_f32_e32 v247, v9, v9
	v_fmac_f32_e32 v254, v2, v2
	v_fmac_f32_e32 v254, v3, v3
	v_fmac_f32_e32 v254, v4, v4
	v_fmac_f32_e32 v254, v5, v5
	v_add_f32_e32 v14, v247, v254
	v_and_b32_e32 v255, 63, v0
	v_xor_b32_e32 v252, 16, v255
	v_xor_b32_e32 v253, 32, v255
	v_lshlrev_b32_e32 v252, 2, v252
	v_lshlrev_b32_e32 v253, 2, v253
	ds_bpermute_b32 v147, v252, v146
	ds_bpermute_b32 v119, v252, v118
	ds_bpermute_b32 v95, v252, v94
	ds_bpermute_b32 v79, v252, v78
	ds_bpermute_b32 v63, v252, v62
	ds_bpermute_b32 v47, v252, v46
	ds_bpermute_b32 v31, v252, v30
	ds_bpermute_b32 v15, v252, v14
	s_waitcnt lgkmcnt(0)
	v_add_f32_e32 v146, v146, v147
	v_add_f32_e32 v118, v118, v119
	v_add_f32_e32 v94, v94, v95
	v_add_f32_e32 v78, v78, v79
	v_add_f32_e32 v62, v62, v63
	v_add_f32_e32 v46, v46, v47
	v_add_f32_e32 v30, v30, v31
	v_add_f32_e32 v14, v14, v15
	ds_bpermute_b32 v147, v253, v146
	ds_bpermute_b32 v119, v253, v118
	ds_bpermute_b32 v95, v253, v94
	ds_bpermute_b32 v79, v253, v78
	ds_bpermute_b32 v63, v253, v62
	ds_bpermute_b32 v47, v253, v46
	ds_bpermute_b32 v31, v253, v30
	ds_bpermute_b32 v15, v253, v14
	s_waitcnt lgkmcnt(0)
	v_add_f32_e32 v146, v146, v147
	v_add_f32_e32 v118, v118, v119
	v_add_f32_e32 v94, v94, v95
	v_add_f32_e32 v78, v78, v79
	v_add_f32_e32 v62, v62, v63
	v_add_f32_e32 v46, v46, v47
	v_add_f32_e32 v30, v30, v31
	v_add_f32_e32 v14, v14, v15
	v_cndmask_b32_e64 v248, 0, v146, s[2:3]
	v_cndmask_b32_e64 v249, 0, v118, s[2:3]
	v_cndmask_b32_e64 v248, v248, v94, s[4:5]
	v_cndmask_b32_e64 v249, v249, v78, s[4:5]
	v_cndmask_b32_e64 v248, v248, v62, s[6:7]
	v_cndmask_b32_e64 v249, v249, v46, s[6:7]
	v_cndmask_b32_e64 v248, v248, v30, s[8:9]
	v_cndmask_b32_e64 v249, v249, v14, s[8:9]
	v_lshl_add_u32 v250, s78, 8, v189
	v_add_u32_e32 v250, v188, v250
	v_lshlrev_b32_e32 v250, 2, v250
	global_atomic_add_f32 v250, v248, s[62:63]
	global_atomic_add_f32 v250, v249, s[62:63] offset:64
	s_andn2_b64 vcc, exec, s[10:11]
	s_mov_b64 s[14:15], -1
	s_cbranch_vccnz .LBB0_781
	s_andn2_b64 vcc, exec, s[0:1]
	s_cbranch_vccnz .LBB0_780
	s_barrier
	s_branch .LBB0_780
